# GEMM group 2 main loop: the 16 per-segment s_setprio toggles replaced by one static priority raise for the wave half that enters one barrier later (reset at phase end)
# speedup vs baseline: 1.0035x; 1.0035x over previous
.LBB0_967:
	s_cmp_eq_u32 s0, 1
	s_cbranch_scc0 .Lg2_noprio
	s_setprio 1

.LBB0_977:
	s_add_i32 s36, s10, 2
	s_add_u32 s37, s8, 0x80
	s_addc_u32 s11, s9, 0
	s_add_i32 s66, 0, 0x10000
	s_cmp_eq_u32 s55, s10
	s_cselect_b32 s11, s1, s11
	s_cselect_b32 s10, s0, s37
	v_add_u32_e32 v0, s66, v156
	s_cselect_b32 s59, s31, s35
	s_cselect_b32 s58, s30, s34
	s_add_i32 s37, 0, 0x14000
	ds_read_b128 v[144:147], v0
	ds_read_b128 v[148:151], v0 offset:1024
	ds_read_b128 v[160:163], v0 offset:2048
	ds_read_b128 v[164:167], v0 offset:3072
	v_add_u32_e32 v0, s37, v156
	ds_read_b128 v[168:171], v0
	ds_read_b128 v[172:175], v0 offset:1024
	ds_read_b128 v[176:179], v0 offset:2048
	ds_read_b128 v[180:183], v0 offset:3072
	v_lshl_add_u64 v[218:219], s[8:9], 0, v[140:141]
	s_add_i32 m0, s48, 0xc000
	ds_read_b128 v[184:187], v158
	ds_read_b128 v[188:191], v158 offset:1024
	ds_read_b128 v[192:195], v158 offset:2048
	ds_read_b128 v[196:199], v158 offset:3072
	ds_read_b128 v[202:205], v158 offset:4096
	ds_read_b128 v[206:209], v158 offset:5120
	ds_read_b128 v[210:213], v158 offset:6144
	ds_read_b128 v[214:217], v158 offset:7168
	global_load_lds_dwordx4 v[218:219], off
	v_lshl_add_u64 v[218:219], s[8:9], 0, v[142:143]
	s_add_i32 m0, s48, 0xe000
	s_nop 0
	global_load_lds_dwordx4 v[218:219], off
	s_waitcnt vmcnt(8)
	s_waitcnt lgkmcnt(0)
	s_barrier
	s_waitcnt lgkmcnt(0)
	v_mfma_f32_16x16x32_bf16 v[126:129], v[144:147], v[184:187], v[126:129]
	v_mfma_f32_16x16x32_bf16 v[122:125], v[160:163], v[184:187], v[122:125]
	v_mfma_f32_16x16x32_bf16 v[110:113], v[144:147], v[192:195], v[110:113]
	v_mfma_f32_16x16x32_bf16 v[106:109], v[160:163], v[192:195], v[106:109]
	v_mfma_f32_16x16x32_bf16 v[94:97], v[144:147], v[202:205], v[94:97]
	v_mfma_f32_16x16x32_bf16 v[90:93], v[160:163], v[202:205], v[90:93]
	v_mfma_f32_16x16x32_bf16 v[78:81], v[144:147], v[210:213], v[78:81]
	v_mfma_f32_16x16x32_bf16 v[74:77], v[160:163], v[210:213], v[74:77]
	v_mfma_f32_16x16x32_bf16 v[126:129], v[148:151], v[188:191], v[126:129]
	v_mfma_f32_16x16x32_bf16 v[122:125], v[164:167], v[188:191], v[122:125]
	v_mfma_f32_16x16x32_bf16 v[110:113], v[148:151], v[196:199], v[110:113]
	v_mfma_f32_16x16x32_bf16 v[106:109], v[164:167], v[196:199], v[106:109]
	v_mfma_f32_16x16x32_bf16 v[94:97], v[148:151], v[206:209], v[94:97]
	v_mfma_f32_16x16x32_bf16 v[90:93], v[164:167], v[206:209], v[90:93]
	v_mfma_f32_16x16x32_bf16 v[78:81], v[148:151], v[214:217], v[78:81]
	v_mfma_f32_16x16x32_bf16 v[74:77], v[164:167], v[214:217], v[74:77]
	v_mfma_f32_16x16x32_bf16 v[118:121], v[168:171], v[184:187], v[118:121]
	v_mfma_f32_16x16x32_bf16 v[114:117], v[176:179], v[184:187], v[114:117]
	v_mfma_f32_16x16x32_bf16 v[102:105], v[168:171], v[192:195], v[102:105]
	v_mfma_f32_16x16x32_bf16 v[98:101], v[176:179], v[192:195], v[98:101]
	v_mfma_f32_16x16x32_bf16 v[86:89], v[168:171], v[202:205], v[86:89]
	v_mfma_f32_16x16x32_bf16 v[82:85], v[176:179], v[202:205], v[82:85]
	v_mfma_f32_16x16x32_bf16 v[70:73], v[168:171], v[210:213], v[70:73]
	v_mfma_f32_16x16x32_bf16 v[66:69], v[176:179], v[210:213], v[66:69]
	v_mfma_f32_16x16x32_bf16 v[118:121], v[172:175], v[188:191], v[118:121]
	v_mfma_f32_16x16x32_bf16 v[114:117], v[180:183], v[188:191], v[114:117]
	v_mfma_f32_16x16x32_bf16 v[102:105], v[172:175], v[196:199], v[102:105]
	v_mfma_f32_16x16x32_bf16 v[98:101], v[180:183], v[196:199], v[98:101]
	v_mfma_f32_16x16x32_bf16 v[86:89], v[172:175], v[206:209], v[86:89]
	v_mfma_f32_16x16x32_bf16 v[82:85], v[180:183], v[206:209], v[82:85]
	v_mfma_f32_16x16x32_bf16 v[70:73], v[172:175], v[214:217], v[70:73]
	v_mfma_f32_16x16x32_bf16 v[66:69], v[180:183], v[214:217], v[66:69]
	s_barrier
	s_add_i32 s66, s66, s47
	v_lshl_add_u64 v[218:219], s[58:59], 0, v[136:137]
	s_mov_b32 m0, s66
	ds_read_b128 v[184:187], v158 offset:16384
	ds_read_b128 v[188:191], v158 offset:17408
	ds_read_b128 v[192:195], v158 offset:18432
	ds_read_b128 v[196:199], v158 offset:19456
	ds_read_b128 v[202:205], v158 offset:20480
	ds_read_b128 v[206:209], v158 offset:21504
	ds_read_b128 v[210:213], v158 offset:22528
	ds_read_b128 v[214:217], v158 offset:23552
	global_load_lds_dwordx4 v[218:219], off
	s_add_i32 m0, s66, 0x2000
	v_lshl_add_u64 v[220:221], s[58:59], 0, v[132:133]
	s_add_u32 s58, s58, s45
	s_addc_u32 s59, s59, 0
	s_add_i32 s37, s37, s47
	global_load_lds_dwordx4 v[220:221], off
	v_lshl_add_u64 v[222:223], s[58:59], 0, v[136:137]
	s_mov_b32 m0, s37
	v_lshl_add_u64 v[224:225], s[58:59], 0, v[132:133]
	global_load_lds_dwordx4 v[222:223], off
	s_add_i32 m0, s37, 0x2000
	v_lshl_add_u64 v[226:227], s[10:11], 0, v[134:135]
	global_load_lds_dwordx4 v[224:225], off
	s_mov_b32 m0, s48
	v_lshl_add_u64 v[228:229], s[10:11], 0, v[130:131]
	global_load_lds_dwordx4 v[226:227], off
	s_mov_b32 m0, s49
	s_nop 0
	global_load_lds_dwordx4 v[228:229], off
	s_waitcnt vmcnt(8)
	s_waitcnt lgkmcnt(0)
	s_barrier
	s_waitcnt lgkmcnt(0)
	v_mfma_f32_16x16x32_bf16 v[62:65], v[144:147], v[184:187], v[62:65]
	v_mfma_f32_16x16x32_bf16 v[58:61], v[160:163], v[184:187], v[58:61]
	v_mfma_f32_16x16x32_bf16 v[46:49], v[144:147], v[192:195], v[46:49]
	v_mfma_f32_16x16x32_bf16 v[42:45], v[160:163], v[192:195], v[42:45]
	v_mfma_f32_16x16x32_bf16 v[30:33], v[144:147], v[202:205], v[30:33]
	v_mfma_f32_16x16x32_bf16 v[26:29], v[160:163], v[202:205], v[26:29]
	v_mfma_f32_16x16x32_bf16 v[14:17], v[144:147], v[210:213], v[14:17]
	v_mfma_f32_16x16x32_bf16 v[10:13], v[160:163], v[210:213], v[10:13]
	v_mfma_f32_16x16x32_bf16 v[62:65], v[148:151], v[188:191], v[62:65]
	v_mfma_f32_16x16x32_bf16 v[58:61], v[164:167], v[188:191], v[58:61]
	v_mfma_f32_16x16x32_bf16 v[46:49], v[148:151], v[196:199], v[46:49]
	v_mfma_f32_16x16x32_bf16 v[42:45], v[164:167], v[196:199], v[42:45]
	v_mfma_f32_16x16x32_bf16 v[30:33], v[148:151], v[206:209], v[30:33]
	v_mfma_f32_16x16x32_bf16 v[26:29], v[164:167], v[206:209], v[26:29]
	v_mfma_f32_16x16x32_bf16 v[14:17], v[148:151], v[214:217], v[14:17]
	v_mfma_f32_16x16x32_bf16 v[10:13], v[164:167], v[214:217], v[10:13]
	v_mfma_f32_16x16x32_bf16 v[54:57], v[168:171], v[184:187], v[54:57]
	v_mfma_f32_16x16x32_bf16 v[50:53], v[176:179], v[184:187], v[50:53]
	v_mfma_f32_16x16x32_bf16 v[38:41], v[168:171], v[192:195], v[38:41]
	v_mfma_f32_16x16x32_bf16 v[34:37], v[176:179], v[192:195], v[34:37]
	v_mfma_f32_16x16x32_bf16 v[22:25], v[168:171], v[202:205], v[22:25]
	v_mfma_f32_16x16x32_bf16 v[18:21], v[176:179], v[202:205], v[18:21]
	v_mfma_f32_16x16x32_bf16 v[6:9], v[168:171], v[210:213], v[6:9]
	v_mfma_f32_16x16x32_bf16 v[2:5], v[176:179], v[210:213], v[2:5]
	v_mfma_f32_16x16x32_bf16 v[54:57], v[172:175], v[188:191], v[54:57]
	v_mfma_f32_16x16x32_bf16 v[50:53], v[180:183], v[188:191], v[50:53]
	v_mfma_f32_16x16x32_bf16 v[38:41], v[172:175], v[196:199], v[38:41]
	v_mfma_f32_16x16x32_bf16 v[34:37], v[180:183], v[196:199], v[34:37]
	v_mfma_f32_16x16x32_bf16 v[22:25], v[172:175], v[206:209], v[22:25]
	v_mfma_f32_16x16x32_bf16 v[18:21], v[180:183], v[206:209], v[18:21]
	v_mfma_f32_16x16x32_bf16 v[6:9], v[172:175], v[214:217], v[6:9]
	v_mfma_f32_16x16x32_bf16 v[2:5], v[180:183], v[214:217], v[2:5]
	s_barrier
	s_add_i32 s37, 0, 0x18000
	v_add_u32_e32 v0, s37, v156
	s_add_i32 s58, 0, 0x1c000
	ds_read_b128 v[144:147], v0
	ds_read_b128 v[148:151], v0 offset:1024
	ds_read_b128 v[160:163], v0 offset:2048
	ds_read_b128 v[164:167], v0 offset:3072
	v_add_u32_e32 v0, s58, v156
	ds_read_b128 v[168:171], v0
	ds_read_b128 v[172:175], v0 offset:1024
	ds_read_b128 v[176:179], v0 offset:2048
	ds_read_b128 v[180:183], v0 offset:3072
	s_add_u32 s10, s10, s12
	s_addc_u32 s11, s11, 0
	s_mov_b32 m0, s50
	v_lshl_add_u64 v[230:231], s[10:11], 0, v[134:135]
	ds_read_b128 v[184:187], v158 offset:32768
	ds_read_b128 v[188:191], v158 offset:33792
	ds_read_b128 v[192:195], v158 offset:34816
	ds_read_b128 v[196:199], v158 offset:35840
	ds_read_b128 v[202:205], v158 offset:36864
	ds_read_b128 v[206:209], v158 offset:37888
	ds_read_b128 v[210:213], v158 offset:38912
	ds_read_b128 v[214:217], v158 offset:39936
	global_load_lds_dwordx4 v[230:231], off
	v_lshl_add_u64 v[230:231], s[10:11], 0, v[130:131]
	s_mov_b32 m0, s51
	s_nop 0
	global_load_lds_dwordx4 v[230:231], off
	s_waitcnt vmcnt(8)
	s_waitcnt lgkmcnt(0)
	s_barrier
	s_waitcnt lgkmcnt(0)
	v_mfma_f32_16x16x32_bf16 v[126:129], v[144:147], v[184:187], v[126:129]
	v_mfma_f32_16x16x32_bf16 v[122:125], v[160:163], v[184:187], v[122:125]
	v_mfma_f32_16x16x32_bf16 v[110:113], v[144:147], v[192:195], v[110:113]
	v_mfma_f32_16x16x32_bf16 v[106:109], v[160:163], v[192:195], v[106:109]
	v_mfma_f32_16x16x32_bf16 v[94:97], v[144:147], v[202:205], v[94:97]
	v_mfma_f32_16x16x32_bf16 v[90:93], v[160:163], v[202:205], v[90:93]
	v_mfma_f32_16x16x32_bf16 v[78:81], v[144:147], v[210:213], v[78:81]
	v_mfma_f32_16x16x32_bf16 v[74:77], v[160:163], v[210:213], v[74:77]
	v_mfma_f32_16x16x32_bf16 v[126:129], v[148:151], v[188:191], v[126:129]
	v_mfma_f32_16x16x32_bf16 v[122:125], v[164:167], v[188:191], v[122:125]
	v_mfma_f32_16x16x32_bf16 v[110:113], v[148:151], v[196:199], v[110:113]
	v_mfma_f32_16x16x32_bf16 v[106:109], v[164:167], v[196:199], v[106:109]
	v_mfma_f32_16x16x32_bf16 v[94:97], v[148:151], v[206:209], v[94:97]
	v_mfma_f32_16x16x32_bf16 v[90:93], v[164:167], v[206:209], v[90:93]
	v_mfma_f32_16x16x32_bf16 v[78:81], v[148:151], v[214:217], v[78:81]
	v_mfma_f32_16x16x32_bf16 v[74:77], v[164:167], v[214:217], v[74:77]
	v_mfma_f32_16x16x32_bf16 v[118:121], v[168:171], v[184:187], v[118:121]
	v_mfma_f32_16x16x32_bf16 v[114:117], v[176:179], v[184:187], v[114:117]
	v_mfma_f32_16x16x32_bf16 v[102:105], v[168:171], v[192:195], v[102:105]
	v_mfma_f32_16x16x32_bf16 v[98:101], v[176:179], v[192:195], v[98:101]
	v_mfma_f32_16x16x32_bf16 v[86:89], v[168:171], v[202:205], v[86:89]
	v_mfma_f32_16x16x32_bf16 v[82:85], v[176:179], v[202:205], v[82:85]
	v_mfma_f32_16x16x32_bf16 v[70:73], v[168:171], v[210:213], v[70:73]
	v_mfma_f32_16x16x32_bf16 v[66:69], v[176:179], v[210:213], v[66:69]
	v_mfma_f32_16x16x32_bf16 v[118:121], v[172:175], v[188:191], v[118:121]
	v_mfma_f32_16x16x32_bf16 v[114:117], v[180:183], v[188:191], v[114:117]
	v_mfma_f32_16x16x32_bf16 v[102:105], v[172:175], v[196:199], v[102:105]
	v_mfma_f32_16x16x32_bf16 v[98:101], v[180:183], v[196:199], v[98:101]
	v_mfma_f32_16x16x32_bf16 v[86:89], v[172:175], v[206:209], v[86:89]
	v_mfma_f32_16x16x32_bf16 v[82:85], v[180:183], v[206:209], v[82:85]
	v_mfma_f32_16x16x32_bf16 v[70:73], v[172:175], v[214:217], v[70:73]
	v_mfma_f32_16x16x32_bf16 v[66:69], v[180:183], v[214:217], v[66:69]
	s_barrier
	s_add_i32 s10, s37, s47
	v_lshl_add_u64 v[218:219], v[218:219], 0, s[14:15]
	s_mov_b32 m0, s10
	ds_read_b128 v[184:187], v158 offset:49152
	ds_read_b128 v[188:191], v158 offset:50176
	ds_read_b128 v[192:195], v158 offset:51200
	ds_read_b128 v[196:199], v158 offset:52224
	ds_read_b128 v[202:205], v158 offset:53248
	ds_read_b128 v[206:209], v158 offset:54272
	ds_read_b128 v[210:213], v158 offset:55296
	ds_read_b128 v[214:217], v158 offset:56320
	global_load_lds_dwordx4 v[218:219], off
	v_lshl_add_u64 v[218:219], v[220:221], 0, s[14:15]
	s_add_i32 m0, s10, 0x2000
	s_add_i32 s10, s58, s47
	global_load_lds_dwordx4 v[218:219], off
	v_lshl_add_u64 v[218:219], v[222:223], 0, s[14:15]
	s_mov_b32 m0, s10
	s_nop 0
	global_load_lds_dwordx4 v[218:219], off
	v_lshl_add_u64 v[218:219], v[224:225], 0, s[14:15]
	s_add_i32 m0, s10, 0x2000
	s_nop 0
	global_load_lds_dwordx4 v[218:219], off
	v_lshl_add_u64 v[218:219], v[226:227], 0, s[14:15]
	s_mov_b32 m0, s53
	s_nop 0
	global_load_lds_dwordx4 v[218:219], off
	v_lshl_add_u64 v[218:219], v[228:229], 0, s[14:15]
	s_mov_b32 m0, s54
	s_nop 0
	global_load_lds_dwordx4 v[218:219], off
	s_waitcnt vmcnt(8)
	s_waitcnt lgkmcnt(0)
	s_barrier
	s_waitcnt lgkmcnt(0)
	v_mfma_f32_16x16x32_bf16 v[62:65], v[144:147], v[184:187], v[62:65]
	v_mfma_f32_16x16x32_bf16 v[58:61], v[160:163], v[184:187], v[58:61]
	v_mfma_f32_16x16x32_bf16 v[46:49], v[144:147], v[192:195], v[46:49]
	v_mfma_f32_16x16x32_bf16 v[42:45], v[160:163], v[192:195], v[42:45]
	v_mfma_f32_16x16x32_bf16 v[30:33], v[144:147], v[202:205], v[30:33]
	v_mfma_f32_16x16x32_bf16 v[26:29], v[160:163], v[202:205], v[26:29]
	v_mfma_f32_16x16x32_bf16 v[14:17], v[144:147], v[210:213], v[14:17]
	v_mfma_f32_16x16x32_bf16 v[10:13], v[160:163], v[210:213], v[10:13]
	v_mfma_f32_16x16x32_bf16 v[62:65], v[148:151], v[188:191], v[62:65]
	v_mfma_f32_16x16x32_bf16 v[58:61], v[164:167], v[188:191], v[58:61]
	v_mfma_f32_16x16x32_bf16 v[46:49], v[148:151], v[196:199], v[46:49]
	v_mfma_f32_16x16x32_bf16 v[42:45], v[164:167], v[196:199], v[42:45]
	v_mfma_f32_16x16x32_bf16 v[30:33], v[148:151], v[206:209], v[30:33]
	v_mfma_f32_16x16x32_bf16 v[26:29], v[164:167], v[206:209], v[26:29]
	v_mfma_f32_16x16x32_bf16 v[14:17], v[148:151], v[214:217], v[14:17]
	v_mfma_f32_16x16x32_bf16 v[10:13], v[164:167], v[214:217], v[10:13]
	v_mfma_f32_16x16x32_bf16 v[54:57], v[168:171], v[184:187], v[54:57]
	v_mfma_f32_16x16x32_bf16 v[50:53], v[176:179], v[184:187], v[50:53]
	v_mfma_f32_16x16x32_bf16 v[38:41], v[168:171], v[192:195], v[38:41]
	v_mfma_f32_16x16x32_bf16 v[34:37], v[176:179], v[192:195], v[34:37]
	v_mfma_f32_16x16x32_bf16 v[22:25], v[168:171], v[202:205], v[22:25]
	v_mfma_f32_16x16x32_bf16 v[18:21], v[176:179], v[202:205], v[18:21]
	v_mfma_f32_16x16x32_bf16 v[6:9], v[168:171], v[210:213], v[6:9]
	v_mfma_f32_16x16x32_bf16 v[2:5], v[176:179], v[210:213], v[2:5]
	v_mfma_f32_16x16x32_bf16 v[54:57], v[172:175], v[188:191], v[54:57]
	v_mfma_f32_16x16x32_bf16 v[50:53], v[180:183], v[188:191], v[50:53]
	v_mfma_f32_16x16x32_bf16 v[38:41], v[172:175], v[196:199], v[38:41]
	v_mfma_f32_16x16x32_bf16 v[34:37], v[180:183], v[196:199], v[34:37]
	v_mfma_f32_16x16x32_bf16 v[22:25], v[172:175], v[206:209], v[22:25]
	v_mfma_f32_16x16x32_bf16 v[18:21], v[180:183], v[206:209], v[18:21]
	v_mfma_f32_16x16x32_bf16 v[6:9], v[172:175], v[214:217], v[6:9]
	v_mfma_f32_16x16x32_bf16 v[2:5], v[180:183], v[214:217], v[2:5]
	s_barrier
	s_add_u32 s8, s8, 0x100
	s_addc_u32 s9, s9, 0
	s_add_u32 s34, s34, 0x100
	s_addc_u32 s35, s35, 0
	s_cmp_ge_u32 s36, s52
	s_mov_b32 s10, s36
	s_cbranch_scc0 .LBB0_977

.LBB0_1081:
	s_setprio 0
	s_waitcnt vmcnt(0)
	s_barrier

.Lg2_first:
	s_mov_b32 s32, 0
	s_add_i32 s36, s10, 2
	s_add_u32 s37, s8, 0x80
	s_addc_u32 s11, s9, 0
	s_add_i32 s66, 0, 0x10000
	s_cmp_eq_u32 s55, s10
	s_cselect_b32 s11, s1, s11
	s_cselect_b32 s10, s0, s37
	v_add_u32_e32 v0, s66, v156
	s_cselect_b32 s59, s31, s35
	s_cselect_b32 s58, s30, s34
	s_add_i32 s37, 0, 0x14000
	ds_read_b128 v[144:147], v0
	ds_read_b128 v[148:151], v0 offset:1024
	ds_read_b128 v[160:163], v0 offset:2048
	ds_read_b128 v[164:167], v0 offset:3072
	v_add_u32_e32 v0, s37, v156
	ds_read_b128 v[168:171], v0
	ds_read_b128 v[172:175], v0 offset:1024
	ds_read_b128 v[176:179], v0 offset:2048
	ds_read_b128 v[180:183], v0 offset:3072
	v_lshl_add_u64 v[218:219], s[8:9], 0, v[140:141]
	s_add_i32 m0, s48, 0xc000
	ds_read_b128 v[184:187], v158
	ds_read_b128 v[188:191], v158 offset:1024
	ds_read_b128 v[192:195], v158 offset:2048
	ds_read_b128 v[196:199], v158 offset:3072
	ds_read_b128 v[202:205], v158 offset:4096
	ds_read_b128 v[206:209], v158 offset:5120
	ds_read_b128 v[210:213], v158 offset:6144
	ds_read_b128 v[214:217], v158 offset:7168
	global_load_lds_dwordx4 v[218:219], off
	v_lshl_add_u64 v[218:219], s[8:9], 0, v[142:143]
	s_add_i32 m0, s48, 0xe000
	s_nop 0
	global_load_lds_dwordx4 v[218:219], off
	s_waitcnt lgkmcnt(0)
	s_barrier
	s_waitcnt lgkmcnt(0)
	v_mfma_f32_16x16x32_bf16 v[126:129], v[144:147], v[184:187], 0
	v_mfma_f32_16x16x32_bf16 v[122:125], v[160:163], v[184:187], 0
	v_mfma_f32_16x16x32_bf16 v[110:113], v[144:147], v[192:195], 0
	v_mfma_f32_16x16x32_bf16 v[106:109], v[160:163], v[192:195], 0
	v_mfma_f32_16x16x32_bf16 v[94:97], v[144:147], v[202:205], 0
	v_mfma_f32_16x16x32_bf16 v[90:93], v[160:163], v[202:205], 0
	v_mfma_f32_16x16x32_bf16 v[78:81], v[144:147], v[210:213], 0
	v_mfma_f32_16x16x32_bf16 v[74:77], v[160:163], v[210:213], 0
	v_mfma_f32_16x16x32_bf16 v[126:129], v[148:151], v[188:191], v[126:129]
	v_mfma_f32_16x16x32_bf16 v[122:125], v[164:167], v[188:191], v[122:125]
	v_mfma_f32_16x16x32_bf16 v[110:113], v[148:151], v[196:199], v[110:113]
	v_mfma_f32_16x16x32_bf16 v[106:109], v[164:167], v[196:199], v[106:109]
	v_mfma_f32_16x16x32_bf16 v[94:97], v[148:151], v[206:209], v[94:97]
	v_mfma_f32_16x16x32_bf16 v[90:93], v[164:167], v[206:209], v[90:93]
	v_mfma_f32_16x16x32_bf16 v[78:81], v[148:151], v[214:217], v[78:81]
	v_mfma_f32_16x16x32_bf16 v[74:77], v[164:167], v[214:217], v[74:77]
	v_mfma_f32_16x16x32_bf16 v[118:121], v[168:171], v[184:187], 0
	v_mfma_f32_16x16x32_bf16 v[114:117], v[176:179], v[184:187], 0
	v_mfma_f32_16x16x32_bf16 v[102:105], v[168:171], v[192:195], 0
	v_mfma_f32_16x16x32_bf16 v[98:101], v[176:179], v[192:195], 0
	v_mfma_f32_16x16x32_bf16 v[86:89], v[168:171], v[202:205], 0
	v_mfma_f32_16x16x32_bf16 v[82:85], v[176:179], v[202:205], 0
	v_mfma_f32_16x16x32_bf16 v[70:73], v[168:171], v[210:213], 0
	v_mfma_f32_16x16x32_bf16 v[66:69], v[176:179], v[210:213], 0
	v_mfma_f32_16x16x32_bf16 v[118:121], v[172:175], v[188:191], v[118:121]
	v_mfma_f32_16x16x32_bf16 v[114:117], v[180:183], v[188:191], v[114:117]
	v_mfma_f32_16x16x32_bf16 v[102:105], v[172:175], v[196:199], v[102:105]
	v_mfma_f32_16x16x32_bf16 v[98:101], v[180:183], v[196:199], v[98:101]
	v_mfma_f32_16x16x32_bf16 v[86:89], v[172:175], v[206:209], v[86:89]
	v_mfma_f32_16x16x32_bf16 v[82:85], v[180:183], v[206:209], v[82:85]
	v_mfma_f32_16x16x32_bf16 v[70:73], v[172:175], v[214:217], v[70:73]
	v_mfma_f32_16x16x32_bf16 v[66:69], v[180:183], v[214:217], v[66:69]
	s_barrier
	s_add_i32 s66, s66, s47
	v_lshl_add_u64 v[218:219], s[58:59], 0, v[136:137]
	s_mov_b32 m0, s66
	ds_read_b128 v[184:187], v158 offset:16384
	ds_read_b128 v[188:191], v158 offset:17408
	ds_read_b128 v[192:195], v158 offset:18432
	ds_read_b128 v[196:199], v158 offset:19456
	ds_read_b128 v[202:205], v158 offset:20480
	ds_read_b128 v[206:209], v158 offset:21504
	ds_read_b128 v[210:213], v158 offset:22528
	ds_read_b128 v[214:217], v158 offset:23552
	global_load_lds_dwordx4 v[218:219], off
	s_add_i32 m0, s66, 0x2000
	v_lshl_add_u64 v[220:221], s[58:59], 0, v[132:133]
	s_add_u32 s58, s58, s45
	s_addc_u32 s59, s59, 0
	s_add_i32 s37, s37, s47
	global_load_lds_dwordx4 v[220:221], off
	v_lshl_add_u64 v[222:223], s[58:59], 0, v[136:137]
	s_mov_b32 m0, s37
	v_lshl_add_u64 v[224:225], s[58:59], 0, v[132:133]
	global_load_lds_dwordx4 v[222:223], off
	s_add_i32 m0, s37, 0x2000
	v_lshl_add_u64 v[226:227], s[10:11], 0, v[134:135]
	global_load_lds_dwordx4 v[224:225], off
	s_mov_b32 m0, s48
	v_lshl_add_u64 v[228:229], s[10:11], 0, v[130:131]
	global_load_lds_dwordx4 v[226:227], off
	s_mov_b32 m0, s49
	s_nop 0
	global_load_lds_dwordx4 v[228:229], off
	s_waitcnt lgkmcnt(0)
	s_barrier
	s_waitcnt lgkmcnt(0)
	v_mfma_f32_16x16x32_bf16 v[62:65], v[144:147], v[184:187], 0
	v_mfma_f32_16x16x32_bf16 v[58:61], v[160:163], v[184:187], 0
	v_mfma_f32_16x16x32_bf16 v[46:49], v[144:147], v[192:195], 0
	v_mfma_f32_16x16x32_bf16 v[42:45], v[160:163], v[192:195], 0
	v_mfma_f32_16x16x32_bf16 v[30:33], v[144:147], v[202:205], 0
	v_mfma_f32_16x16x32_bf16 v[26:29], v[160:163], v[202:205], 0
	v_mfma_f32_16x16x32_bf16 v[14:17], v[144:147], v[210:213], 0
	v_mfma_f32_16x16x32_bf16 v[10:13], v[160:163], v[210:213], 0
	v_mfma_f32_16x16x32_bf16 v[62:65], v[148:151], v[188:191], v[62:65]
	v_mfma_f32_16x16x32_bf16 v[58:61], v[164:167], v[188:191], v[58:61]
	v_mfma_f32_16x16x32_bf16 v[46:49], v[148:151], v[196:199], v[46:49]
	v_mfma_f32_16x16x32_bf16 v[42:45], v[164:167], v[196:199], v[42:45]
	v_mfma_f32_16x16x32_bf16 v[30:33], v[148:151], v[206:209], v[30:33]
	v_mfma_f32_16x16x32_bf16 v[26:29], v[164:167], v[206:209], v[26:29]
	v_mfma_f32_16x16x32_bf16 v[14:17], v[148:151], v[214:217], v[14:17]
	v_mfma_f32_16x16x32_bf16 v[10:13], v[164:167], v[214:217], v[10:13]
	v_mfma_f32_16x16x32_bf16 v[54:57], v[168:171], v[184:187], 0
	v_mfma_f32_16x16x32_bf16 v[50:53], v[176:179], v[184:187], 0
	v_mfma_f32_16x16x32_bf16 v[38:41], v[168:171], v[192:195], 0
	v_mfma_f32_16x16x32_bf16 v[34:37], v[176:179], v[192:195], 0
	v_mfma_f32_16x16x32_bf16 v[22:25], v[168:171], v[202:205], 0
	v_mfma_f32_16x16x32_bf16 v[18:21], v[176:179], v[202:205], 0
	v_mfma_f32_16x16x32_bf16 v[6:9], v[168:171], v[210:213], 0
	v_mfma_f32_16x16x32_bf16 v[2:5], v[176:179], v[210:213], 0
	v_mfma_f32_16x16x32_bf16 v[54:57], v[172:175], v[188:191], v[54:57]
	v_mfma_f32_16x16x32_bf16 v[50:53], v[180:183], v[188:191], v[50:53]
	v_mfma_f32_16x16x32_bf16 v[38:41], v[172:175], v[196:199], v[38:41]
	v_mfma_f32_16x16x32_bf16 v[34:37], v[180:183], v[196:199], v[34:37]
	v_mfma_f32_16x16x32_bf16 v[22:25], v[172:175], v[206:209], v[22:25]
	v_mfma_f32_16x16x32_bf16 v[18:21], v[180:183], v[206:209], v[18:21]
	v_mfma_f32_16x16x32_bf16 v[6:9], v[172:175], v[214:217], v[6:9]
	v_mfma_f32_16x16x32_bf16 v[2:5], v[180:183], v[214:217], v[2:5]
	s_barrier
	s_add_i32 s37, 0, 0x18000
	v_add_u32_e32 v0, s37, v156
	s_add_i32 s58, 0, 0x1c000
	ds_read_b128 v[144:147], v0
	ds_read_b128 v[148:151], v0 offset:1024
	ds_read_b128 v[160:163], v0 offset:2048
	ds_read_b128 v[164:167], v0 offset:3072
	v_add_u32_e32 v0, s58, v156
	ds_read_b128 v[168:171], v0
	ds_read_b128 v[172:175], v0 offset:1024
	ds_read_b128 v[176:179], v0 offset:2048
	ds_read_b128 v[180:183], v0 offset:3072
	s_add_u32 s10, s10, s12
	s_addc_u32 s11, s11, 0
	s_mov_b32 m0, s50
	v_lshl_add_u64 v[230:231], s[10:11], 0, v[134:135]
	ds_read_b128 v[184:187], v158 offset:32768
	ds_read_b128 v[188:191], v158 offset:33792
	ds_read_b128 v[192:195], v158 offset:34816
	ds_read_b128 v[196:199], v158 offset:35840
	ds_read_b128 v[202:205], v158 offset:36864
	ds_read_b128 v[206:209], v158 offset:37888
	ds_read_b128 v[210:213], v158 offset:38912
	ds_read_b128 v[214:217], v158 offset:39936
	global_load_lds_dwordx4 v[230:231], off
	v_lshl_add_u64 v[230:231], s[10:11], 0, v[130:131]
	s_mov_b32 m0, s51
	s_nop 0
	global_load_lds_dwordx4 v[230:231], off
	s_waitcnt vmcnt(8)
	s_waitcnt lgkmcnt(0)
	s_barrier
	s_waitcnt lgkmcnt(0)
	v_mfma_f32_16x16x32_bf16 v[126:129], v[144:147], v[184:187], v[126:129]
	v_mfma_f32_16x16x32_bf16 v[122:125], v[160:163], v[184:187], v[122:125]
	v_mfma_f32_16x16x32_bf16 v[110:113], v[144:147], v[192:195], v[110:113]
	v_mfma_f32_16x16x32_bf16 v[106:109], v[160:163], v[192:195], v[106:109]
	v_mfma_f32_16x16x32_bf16 v[94:97], v[144:147], v[202:205], v[94:97]
	v_mfma_f32_16x16x32_bf16 v[90:93], v[160:163], v[202:205], v[90:93]
	v_mfma_f32_16x16x32_bf16 v[78:81], v[144:147], v[210:213], v[78:81]
	v_mfma_f32_16x16x32_bf16 v[74:77], v[160:163], v[210:213], v[74:77]
	v_mfma_f32_16x16x32_bf16 v[126:129], v[148:151], v[188:191], v[126:129]
	v_mfma_f32_16x16x32_bf16 v[122:125], v[164:167], v[188:191], v[122:125]
	v_mfma_f32_16x16x32_bf16 v[110:113], v[148:151], v[196:199], v[110:113]
	v_mfma_f32_16x16x32_bf16 v[106:109], v[164:167], v[196:199], v[106:109]
	v_mfma_f32_16x16x32_bf16 v[94:97], v[148:151], v[206:209], v[94:97]
	v_mfma_f32_16x16x32_bf16 v[90:93], v[164:167], v[206:209], v[90:93]
	v_mfma_f32_16x16x32_bf16 v[78:81], v[148:151], v[214:217], v[78:81]
	v_mfma_f32_16x16x32_bf16 v[74:77], v[164:167], v[214:217], v[74:77]
	v_mfma_f32_16x16x32_bf16 v[118:121], v[168:171], v[184:187], v[118:121]
	v_mfma_f32_16x16x32_bf16 v[114:117], v[176:179], v[184:187], v[114:117]
	v_mfma_f32_16x16x32_bf16 v[102:105], v[168:171], v[192:195], v[102:105]
	v_mfma_f32_16x16x32_bf16 v[98:101], v[176:179], v[192:195], v[98:101]
	v_mfma_f32_16x16x32_bf16 v[86:89], v[168:171], v[202:205], v[86:89]
	v_mfma_f32_16x16x32_bf16 v[82:85], v[176:179], v[202:205], v[82:85]
	v_mfma_f32_16x16x32_bf16 v[70:73], v[168:171], v[210:213], v[70:73]
	v_mfma_f32_16x16x32_bf16 v[66:69], v[176:179], v[210:213], v[66:69]
	v_mfma_f32_16x16x32_bf16 v[118:121], v[172:175], v[188:191], v[118:121]
	v_mfma_f32_16x16x32_bf16 v[114:117], v[180:183], v[188:191], v[114:117]
	v_mfma_f32_16x16x32_bf16 v[102:105], v[172:175], v[196:199], v[102:105]
	v_mfma_f32_16x16x32_bf16 v[98:101], v[180:183], v[196:199], v[98:101]
	v_mfma_f32_16x16x32_bf16 v[86:89], v[172:175], v[206:209], v[86:89]
	v_mfma_f32_16x16x32_bf16 v[82:85], v[180:183], v[206:209], v[82:85]
	v_mfma_f32_16x16x32_bf16 v[70:73], v[172:175], v[214:217], v[70:73]
	v_mfma_f32_16x16x32_bf16 v[66:69], v[180:183], v[214:217], v[66:69]
	s_barrier
	s_add_i32 s10, s37, s47
	v_lshl_add_u64 v[218:219], v[218:219], 0, s[14:15]
	s_mov_b32 m0, s10
	ds_read_b128 v[184:187], v158 offset:49152
	ds_read_b128 v[188:191], v158 offset:50176
	ds_read_b128 v[192:195], v158 offset:51200
	ds_read_b128 v[196:199], v158 offset:52224
	ds_read_b128 v[202:205], v158 offset:53248
	ds_read_b128 v[206:209], v158 offset:54272
	ds_read_b128 v[210:213], v158 offset:55296
	ds_read_b128 v[214:217], v158 offset:56320
	global_load_lds_dwordx4 v[218:219], off
	v_lshl_add_u64 v[218:219], v[220:221], 0, s[14:15]
	s_add_i32 m0, s10, 0x2000
	s_add_i32 s10, s58, s47
	global_load_lds_dwordx4 v[218:219], off
	v_lshl_add_u64 v[218:219], v[222:223], 0, s[14:15]
	s_mov_b32 m0, s10
	s_nop 0
	global_load_lds_dwordx4 v[218:219], off
	v_lshl_add_u64 v[218:219], v[224:225], 0, s[14:15]
	s_add_i32 m0, s10, 0x2000
	s_nop 0
	global_load_lds_dwordx4 v[218:219], off
	v_lshl_add_u64 v[218:219], v[226:227], 0, s[14:15]
	s_mov_b32 m0, s53
	s_nop 0
	global_load_lds_dwordx4 v[218:219], off
	v_lshl_add_u64 v[218:219], v[228:229], 0, s[14:15]
	s_mov_b32 m0, s54
	s_nop 0
	global_load_lds_dwordx4 v[218:219], off
	s_waitcnt vmcnt(8)
	s_waitcnt lgkmcnt(0)
	s_barrier
	s_waitcnt lgkmcnt(0)
	v_mfma_f32_16x16x32_bf16 v[62:65], v[144:147], v[184:187], v[62:65]
	v_mfma_f32_16x16x32_bf16 v[58:61], v[160:163], v[184:187], v[58:61]
	v_mfma_f32_16x16x32_bf16 v[46:49], v[144:147], v[192:195], v[46:49]
	v_mfma_f32_16x16x32_bf16 v[42:45], v[160:163], v[192:195], v[42:45]
	v_mfma_f32_16x16x32_bf16 v[30:33], v[144:147], v[202:205], v[30:33]
	v_mfma_f32_16x16x32_bf16 v[26:29], v[160:163], v[202:205], v[26:29]
	v_mfma_f32_16x16x32_bf16 v[14:17], v[144:147], v[210:213], v[14:17]
	v_mfma_f32_16x16x32_bf16 v[10:13], v[160:163], v[210:213], v[10:13]
	v_mfma_f32_16x16x32_bf16 v[62:65], v[148:151], v[188:191], v[62:65]
	v_mfma_f32_16x16x32_bf16 v[58:61], v[164:167], v[188:191], v[58:61]
	v_mfma_f32_16x16x32_bf16 v[46:49], v[148:151], v[196:199], v[46:49]
	v_mfma_f32_16x16x32_bf16 v[42:45], v[164:167], v[196:199], v[42:45]
	v_mfma_f32_16x16x32_bf16 v[30:33], v[148:151], v[206:209], v[30:33]
	v_mfma_f32_16x16x32_bf16 v[26:29], v[164:167], v[206:209], v[26:29]
	v_mfma_f32_16x16x32_bf16 v[14:17], v[148:151], v[214:217], v[14:17]
	v_mfma_f32_16x16x32_bf16 v[10:13], v[164:167], v[214:217], v[10:13]
	v_mfma_f32_16x16x32_bf16 v[54:57], v[168:171], v[184:187], v[54:57]
	v_mfma_f32_16x16x32_bf16 v[50:53], v[176:179], v[184:187], v[50:53]
	v_mfma_f32_16x16x32_bf16 v[38:41], v[168:171], v[192:195], v[38:41]
	v_mfma_f32_16x16x32_bf16 v[34:37], v[176:179], v[192:195], v[34:37]
	v_mfma_f32_16x16x32_bf16 v[22:25], v[168:171], v[202:205], v[22:25]
	v_mfma_f32_16x16x32_bf16 v[18:21], v[176:179], v[202:205], v[18:21]
	v_mfma_f32_16x16x32_bf16 v[6:9], v[168:171], v[210:213], v[6:9]
	v_mfma_f32_16x16x32_bf16 v[2:5], v[176:179], v[210:213], v[2:5]
	v_mfma_f32_16x16x32_bf16 v[54:57], v[172:175], v[188:191], v[54:57]
	v_mfma_f32_16x16x32_bf16 v[50:53], v[180:183], v[188:191], v[50:53]
	v_mfma_f32_16x16x32_bf16 v[38:41], v[172:175], v[196:199], v[38:41]
	v_mfma_f32_16x16x32_bf16 v[34:37], v[180:183], v[196:199], v[34:37]
	v_mfma_f32_16x16x32_bf16 v[22:25], v[172:175], v[206:209], v[22:25]
	v_mfma_f32_16x16x32_bf16 v[18:21], v[180:183], v[206:209], v[18:21]
	v_mfma_f32_16x16x32_bf16 v[6:9], v[172:175], v[214:217], v[6:9]
	v_mfma_f32_16x16x32_bf16 v[2:5], v[180:183], v[214:217], v[2:5]
	s_barrier
	s_add_u32 s8, s8, 0x100
	s_addc_u32 s9, s9, 0
	s_add_u32 s34, s34, 0x100
	s_addc_u32 s35, s35, 0
	s_cmp_ge_u32 s36, s52
	s_mov_b32 s10, s36
	s_cbranch_scc0 .LBB0_977
	s_branch .Lg2_after
